# scan chunk hand-scheduled: batched operand reads, interleaved output accumulators, batched partial-sum reads
# baseline (speedup 1.0000x reference)
.LBB0_92:
	s_or_b64 exec, exec, s[24:25]
	v_add_u32_e32 v93, s43, v78
	ds_read_b128 v[124:127], v93
	ds_read_b128 v[140:143], v110
	ds_read_b128 v[156:159], v110 offset:64
	ds_read_b128 v[128:131], v93 offset:64
	ds_read_b128 v[144:147], v110 offset:2304
	ds_read_b128 v[160:163], v110 offset:2368
	ds_read_b128 v[132:135], v93 offset:128
	ds_read_b128 v[148:151], v110 offset:4608
	ds_read_b128 v[192:195], v110 offset:4672
	ds_read_b128 v[136:139], v93 offset:192
	ds_read_b128 v[152:155], v110 offset:6912
	ds_read_b128 v[196:199], v110 offset:6976
	s_mov_b32 s4, 0x3d800000
	v_add_u32_e32 v164, 0x9000, v111
	v_add_u32_e32 v166, 0xb000, v111
	v_add_u32_e32 v168, 0xd000, v111
	v_add_u32_e32 v169, 0xf000, v111
	v_add_u32_e32 v170, s44, v80
	v_add_u32_e32 v172, s45, v80
	s_waitcnt vmcnt(11) lgkmcnt(9)
	v_pk_mul_f32 v[24:25], v[24:25], v[124:125]
	v_pk_mul_f32 v[26:27], v[26:27], v[126:127]
	s_nop 1
	v_mfma_f32_16x16x32_bf16 v[24:27], v[140:143], v[68:71], v[24:27]
	s_waitcnt vmcnt(10)
	v_mfma_f32_16x16x32_bf16 v[24:27], v[156:159], v[72:75], v[24:27]
	s_waitcnt lgkmcnt(6)
	v_pk_mul_f32 v[12:13], v[12:13], v[128:129]
	v_pk_mul_f32 v[14:15], v[14:15], v[130:131]
	s_nop 1
	v_mfma_f32_16x16x32_bf16 v[12:15], v[144:147], v[68:71], v[12:15]
	v_mfma_f32_16x16x32_bf16 v[12:15], v[160:163], v[72:75], v[12:15]
	ds_read2_b64 v[200:203], v164 offset1:4
	ds_read2_b64 v[204:207], v164 offset0:8 offset1:12
	ds_read2_b64 v[208:211], v166 offset0:32 offset1:36
	ds_read2_b64 v[212:215], v166 offset0:40 offset1:44
	ds_read2_b64 v[216:219], v168 offset0:64 offset1:68
	ds_read2_b64 v[220:223], v168 offset0:72 offset1:76
	ds_read2_b64 v[224:227], v169 offset0:96 offset1:100
	ds_read2_b64 v[228:231], v169 offset0:104 offset1:108
	s_waitcnt lgkmcnt(11)
	v_pk_mul_f32 v[4:5], v[4:5], v[132:133]
	v_pk_mul_f32 v[6:7], v[6:7], v[134:135]
	s_nop 1
	v_mfma_f32_16x16x32_bf16 v[4:7], v[148:151], v[68:71], v[4:7]
	v_mfma_f32_16x16x32_bf16 v[4:7], v[192:195], v[72:75], v[4:7]
	s_waitcnt lgkmcnt(8)
	v_pk_mul_f32 v[0:1], v[0:1], v[136:137]
	v_pk_mul_f32 v[2:3], v[2:3], v[138:139]
	s_nop 1
	v_mfma_f32_16x16x32_bf16 v[0:3], v[152:155], v[68:71], v[0:3]
	v_mfma_f32_16x16x32_bf16 v[0:3], v[196:199], v[72:75], v[0:3]
	s_nop 3
	v_cvt_pk_bf16_f32 v112, v24, v25
	v_cvt_pk_bf16_f32 v113, v26, v27
	v_cvt_pk_bf16_f32 v114, v12, v13
	v_cvt_pk_bf16_f32 v115, v14, v15
	s_nop 1
	s_waitcnt lgkmcnt(7)
	v_mfma_f32_16x16x32_bf16 v[232:235], v[112:115], v[200:203], 0
	s_waitcnt lgkmcnt(5)
	v_mfma_f32_16x16x32_bf16 v[236:239], v[112:115], v[208:211], 0
	s_waitcnt lgkmcnt(3)
	v_mfma_f32_16x16x32_bf16 v[240:243], v[112:115], v[216:219], 0
	s_waitcnt lgkmcnt(1)
	v_mfma_f32_16x16x32_bf16 v[244:247], v[112:115], v[224:227], 0
	v_cvt_pk_bf16_f32 v116, v4, v5
	v_cvt_pk_bf16_f32 v117, v6, v7
	v_cvt_pk_bf16_f32 v118, v0, v1
	v_cvt_pk_bf16_f32 v119, v2, v3
	s_waitcnt lgkmcnt(0)
	s_nop 0
	v_mfma_f32_16x16x32_bf16 v[232:235], v[116:119], v[204:207], v[232:235]
	v_mfma_f32_16x16x32_bf16 v[236:239], v[116:119], v[212:215], v[236:239]
	v_mfma_f32_16x16x32_bf16 v[240:243], v[116:119], v[220:223], v[240:243]
	v_mfma_f32_16x16x32_bf16 v[244:247], v[116:119], v[228:231], v[244:247]
	v_add_u32_e32 v68, s44, v80
	v_add_u32_e32 v69, 0x9000, v111
	v_add_u32_e32 v70, 0xb000, v111
	v_add_u32_e32 v71, 0xd000, v111
	v_add_u32_e32 v72, 0xf000, v111
	v_add_u32_e32 v73, s45, v80
	s_nop 1
	ds_write_b128 v170, v[232:235]
	ds_write_b128 v170, v[236:239] offset:1024
	ds_write_b128 v170, v[240:243] offset:2048
	ds_write_b128 v170, v[244:247] offset:3072
	s_waitcnt lgkmcnt(0)
	s_barrier
	ds_read_b128 v[124:127], v172
	ds_read_b128 v[128:131], v172 offset:8192
	ds_read_b128 v[132:135], v172 offset:16384
	ds_read_b128 v[136:139], v172 offset:24576
	s_waitcnt lgkmcnt(2)
	v_pk_add_f32 v[74:75], v[126:127], v[130:131]
	v_pk_add_f32 v[116:117], v[124:125], v[128:129]
	s_waitcnt lgkmcnt(1)
	v_pk_add_f32 v[74:75], v[74:75], v[134:135]
	v_pk_add_f32 v[116:117], v[116:117], v[132:133]
	s_waitcnt lgkmcnt(0)
	v_pk_add_f32 v[74:75], v[74:75], v[138:139]
	v_pk_add_f32 v[112:113], v[116:117], v[136:137]
	v_pk_mul_f32 v[74:75], v[74:75], s[4:5] op_sel_hi:[1,0]
	v_pk_mul_f32 v[112:113], v[112:113], s[4:5] op_sel_hi:[1,0]
	s_nop 0
	v_cvt_pk_bf16_f32 v112, v112, v113
	v_cvt_pk_bf16_f32 v113, v74, v75
	v_add_u32_e32 v74, s34, v33
	v_ashrrev_i32_e32 v75, 31, v74
	v_lshlrev_b64 v[74:75], 12, v[74:75]
	v_lshl_add_u64 v[74:75], v[34:35], 0, v[74:75]
	global_store_dwordx2 v[74:75], v[112:113], off
	s_waitcnt vmcnt(10)
	ds_write_b128 v79, v[28:31]
	s_waitcnt vmcnt(9)
	ds_write_b128 v81, v[40:43] offset:36864
	s_waitcnt vmcnt(8)
	ds_write_b128 v79, v[44:47] offset:9216
	s_waitcnt vmcnt(7)
	ds_write_b128 v81, v[48:51] offset:45312
	s_waitcnt vmcnt(6)
	ds_write_b128 v79, v[52:55] offset:18432
	s_waitcnt vmcnt(5)
	ds_write_b128 v81, v[56:59] offset:53760
	s_waitcnt vmcnt(4)
	ds_write_b128 v79, v[60:63] offset:27648
	s_waitcnt vmcnt(3)
	ds_write_b128 v81, v[64:67] offset:62208
	s_and_saveexec_b64 s[24:25], s[2:3]
	s_cbranch_execz .LBB0_94
	s_waitcnt vmcnt(1)
	ds_write_b128 v91, v[8:11]
